# v36 + FFN1 SwiGLU epilogue list-scheduled: 64 exp/rcp chains interleaved through 32 dead fragment registers (10 nops instead of 117, no serial transcendental latency)
# baseline (speedup 1.0000x reference)
; __device__ __forceinline__ unsigned cvt_pk_bf16(float lo, float hi) { unsigned r; asm volatile("v_cvt_pk_bf16_f32 %0, %1, %2" : "=v"(r) : "v"(lo), "v"(hi)); return r; }
;     DI void operator()(const pg8::f32x4 (&acc)[2][2][4][2], const pg8::Unit& u, int wr, int wc, int fr, int fq) const {
;         const int row0 = u.pm * 256 + wr * 64 + fr, col0 = u.pn * 128 + wc * 32 + 8 * fq;
; #pragma unroll
;         for (int ai = 0; ai < 2; ++ai)
; #pragma unroll
;             for (int m = 0; m < 4; ++m) { bf16* rowp = O + (size_t)(row0 + ai * 128 + m * 16) * FF + col0;
;                 float hv[8];
; #pragma unroll
;                 for (int n = 0; n < 2; ++n)
; #pragma unroll
;                     for (int j = 0; j < 4; ++j) { const float g = acc[ai][0][m][n][j], up = acc[ai][1][m][n][j]; hv[4 * n + j] = g * __builtin_amdgcn_rcpf(1.f + __expf(-g)) * up; }
;                 v4u w; w.x = pg8::cvt_pk_bf16(hv[0], hv[1]); w.y = pg8::cvt_pk_bf16(hv[2], hv[3]); w.z = pg8::cvt_pk_bf16(hv[4], hv[5]); w.w = pg8::cvt_pk_bf16(hv[6], hv[7]);
;                 *(v4u*)rowp = w; }
.LBB0_1179:
	v_mul_f32_e32 v150, 0xbfb8aa3b, v124
	v_lshl_or_b32 v146, s33, 7, v142
	v_lshl_add_u32 v144, s34, 8, v140
	v_mov_b64_e32 v[138:139], s[2:3]
	s_movk_i32 s7, 0x1600
	v_mul_f32_e32 v151, 0xbfb8aa3b, v125
	s_andn2_b64 vcc, exec, s[42:43]
	v_mul_f32_e32 v152, 0xbfb8aa3b, v126
	v_mul_f32_e32 v153, 0xbfb8aa3b, v127
	v_mul_f32_e32 v154, 0xbfb8aa3b, v116
	v_mul_f32_e32 v155, 0xbfb8aa3b, v117
	v_mul_f32_e32 v156, 0xbfb8aa3b, v118
	v_mul_f32_e32 v157, 0xbfb8aa3b, v119
	v_mul_f32_e32 v158, 0xbfb8aa3b, v108
	v_mul_f32_e32 v159, 0xbfb8aa3b, v109
	v_mul_f32_e32 v160, 0xbfb8aa3b, v110
	v_mul_f32_e32 v161, 0xbfb8aa3b, v111
	v_mul_f32_e32 v162, 0xbfb8aa3b, v100
	v_mul_f32_e32 v163, 0xbfb8aa3b, v101
	v_mul_f32_e32 v164, 0xbfb8aa3b, v102
	v_mul_f32_e32 v165, 0xbfb8aa3b, v103
	v_mul_f32_e32 v166, 0xbfb8aa3b, v92
	v_mul_f32_e32 v167, 0xbfb8aa3b, v93
	v_mul_f32_e32 v168, 0xbfb8aa3b, v94
	v_mul_f32_e32 v169, 0xbfb8aa3b, v95
	v_mul_f32_e32 v170, 0xbfb8aa3b, v84
	v_mul_f32_e32 v171, 0xbfb8aa3b, v85
	v_mul_f32_e32 v172, 0xbfb8aa3b, v86
	v_mul_f32_e32 v173, 0xbfb8aa3b, v87
	v_mul_f32_e32 v174, 0xbfb8aa3b, v76
	v_mul_f32_e32 v175, 0xbfb8aa3b, v77
	v_mul_f32_e32 v176, 0xbfb8aa3b, v78
	v_mul_f32_e32 v177, 0xbfb8aa3b, v79
	v_mul_f32_e32 v178, 0xbfb8aa3b, v68
	v_mul_f32_e32 v179, 0xbfb8aa3b, v69
	v_mul_f32_e32 v180, 0xbfb8aa3b, v70
	v_mul_f32_e32 v181, 0xbfb8aa3b, v71
	v_exp_f32_e32 v150, v150
	v_ashrrev_i32_e32 v147, 31, v146
	v_mad_i64_i32 v[148:149], s[14:15], v144, s7, v[138:139]
	v_exp_f32_e32 v151, v151
	v_exp_f32_e32 v152, v152
	v_exp_f32_e32 v153, v153
	v_exp_f32_e32 v154, v154
	v_exp_f32_e32 v155, v155
	v_exp_f32_e32 v156, v156
	v_exp_f32_e32 v157, v157
	v_exp_f32_e32 v158, v158
	v_exp_f32_e32 v159, v159
	v_exp_f32_e32 v160, v160
	v_exp_f32_e32 v161, v161
	v_exp_f32_e32 v162, v162
	v_exp_f32_e32 v163, v163
	v_exp_f32_e32 v164, v164
	v_exp_f32_e32 v165, v165
	v_exp_f32_e32 v166, v166
	v_exp_f32_e32 v167, v167
	v_exp_f32_e32 v168, v168
	v_exp_f32_e32 v169, v169
	v_exp_f32_e32 v170, v170
	v_exp_f32_e32 v171, v171
	v_exp_f32_e32 v172, v172
	v_exp_f32_e32 v173, v173
	v_exp_f32_e32 v174, v174
	v_exp_f32_e32 v175, v175
	v_exp_f32_e32 v176, v176
	v_exp_f32_e32 v177, v177
	v_exp_f32_e32 v178, v178
	v_exp_f32_e32 v179, v179
	v_exp_f32_e32 v180, v180
	v_exp_f32_e32 v181, v181
	v_add_f32_e32 v150, 1.0, v150
	v_add_f32_e32 v151, 1.0, v151
	v_add_f32_e32 v152, 1.0, v152
	v_add_f32_e32 v153, 1.0, v153
	v_add_f32_e32 v154, 1.0, v154
	v_add_f32_e32 v155, 1.0, v155
	v_add_f32_e32 v156, 1.0, v156
	v_add_f32_e32 v157, 1.0, v157
	v_add_f32_e32 v158, 1.0, v158
	v_add_f32_e32 v159, 1.0, v159
	v_add_f32_e32 v160, 1.0, v160
	v_add_f32_e32 v161, 1.0, v161
	v_add_f32_e32 v162, 1.0, v162
	v_add_f32_e32 v163, 1.0, v163
	v_add_f32_e32 v164, 1.0, v164
	v_add_f32_e32 v165, 1.0, v165
	v_add_f32_e32 v166, 1.0, v166
	v_add_f32_e32 v167, 1.0, v167
	v_add_f32_e32 v168, 1.0, v168
	v_add_f32_e32 v169, 1.0, v169
	v_add_f32_e32 v170, 1.0, v170
	v_add_f32_e32 v171, 1.0, v171
	v_add_f32_e32 v172, 1.0, v172
	v_add_f32_e32 v173, 1.0, v173
	v_add_f32_e32 v174, 1.0, v174
	v_add_f32_e32 v175, 1.0, v175
	v_add_f32_e32 v176, 1.0, v176
	v_add_f32_e32 v177, 1.0, v177
	v_add_f32_e32 v178, 1.0, v178
	v_add_f32_e32 v179, 1.0, v179
	v_add_f32_e32 v180, 1.0, v180
	v_add_f32_e32 v181, 1.0, v181
	v_rcp_f32_e32 v150, v150
	v_rcp_f32_e32 v151, v151
	v_rcp_f32_e32 v152, v152
	v_rcp_f32_e32 v153, v153
	v_rcp_f32_e32 v154, v154
	v_rcp_f32_e32 v155, v155
	v_rcp_f32_e32 v156, v156
	v_rcp_f32_e32 v157, v157
	v_rcp_f32_e32 v158, v158
	v_rcp_f32_e32 v159, v159
	v_rcp_f32_e32 v160, v160
	v_rcp_f32_e32 v161, v161
	v_rcp_f32_e32 v162, v162
	v_rcp_f32_e32 v163, v163
	v_rcp_f32_e32 v164, v164
	v_rcp_f32_e32 v165, v165
	v_rcp_f32_e32 v166, v166
	v_rcp_f32_e32 v167, v167
	v_rcp_f32_e32 v168, v168
	v_rcp_f32_e32 v169, v169
	v_rcp_f32_e32 v170, v170
	v_rcp_f32_e32 v171, v171
	v_rcp_f32_e32 v172, v172
	v_rcp_f32_e32 v173, v173
	v_rcp_f32_e32 v174, v174
	v_rcp_f32_e32 v175, v175
	v_rcp_f32_e32 v176, v176
	v_rcp_f32_e32 v177, v177
	v_rcp_f32_e32 v178, v178
	v_rcp_f32_e32 v179, v179
	v_rcp_f32_e32 v180, v180
	v_rcp_f32_e32 v181, v181
	v_mul_f32_e32 v124, v124, v150
	v_mul_f32_e32 v151, v125, v151
	v_mul_f32_e32 v152, v126, v152
	v_mul_f32_e32 v153, v127, v153
	v_mul_f32_e32 v116, v116, v154
	v_mul_f32_e32 v155, v117, v155
	v_mul_f32_e32 v156, v118, v156
	v_mul_f32_e32 v157, v119, v157
	v_mul_f32_e32 v108, v108, v158
	v_mul_f32_e32 v159, v109, v159
	v_mul_f32_e32 v160, v110, v160
	v_mul_f32_e32 v161, v111, v161
	v_mul_f32_e32 v100, v100, v162
	v_mul_f32_e32 v163, v101, v163
	v_mul_f32_e32 v164, v102, v164
	v_mul_f32_e32 v165, v103, v165
	v_mul_f32_e32 v92, v92, v166
	v_mul_f32_e32 v167, v93, v167
	v_mul_f32_e32 v168, v94, v168
	v_mul_f32_e32 v169, v95, v169
	v_mul_f32_e32 v84, v84, v170
	v_mul_f32_e32 v171, v85, v171
	v_mul_f32_e32 v172, v86, v172
	v_mul_f32_e32 v173, v87, v173
	v_mul_f32_e32 v76, v76, v174
	v_mul_f32_e32 v175, v77, v175
	v_mul_f32_e32 v176, v78, v176
	v_mul_f32_e32 v177, v79, v177
	v_mul_f32_e32 v68, v68, v178
	v_mul_f32_e32 v179, v69, v179
	v_mul_f32_e32 v180, v70, v180
	v_mul_f32_e32 v181, v71, v181
	v_mul_f32_e32 v120, v124, v120
	v_mul_f32_e32 v121, v151, v121
	v_mul_f32_e32 v122, v152, v122
	v_mul_f32_e32 v123, v153, v123
	v_mul_f32_e32 v116, v116, v112
	v_mul_f32_e32 v117, v155, v113
	v_mul_f32_e32 v125, v157, v115
	v_mul_f32_e32 v104, v108, v104
	v_mul_f32_e32 v105, v159, v105
	v_mul_f32_e32 v106, v160, v106
	v_mul_f32_e32 v107, v161, v107
	v_mul_f32_e32 v109, v163, v97
	v_mul_f32_e32 v102, v164, v98
	v_mul_f32_e32 v99, v165, v99
	v_mul_f32_e32 v88, v92, v88
	v_mul_f32_e32 v89, v167, v89
; __device__ __forceinline__ unsigned cvt_pk_bf16(float lo, float hi) { unsigned r; asm volatile("v_cvt_pk_bf16_f32 %0, %1, %2" : "=v"(r) : "v"(lo), "v"(hi)); return r; }
;     DI void operator()(const pg8::f32x4 (&acc)[2][2][4][2], const pg8::Unit& u, int wr, int wc, int fr, int fq) const {
;         const int row0 = u.pm * 256 + wr * 64 + fr, col0 = u.pn * 128 + wc * 32 + 8 * fq;
; #pragma unroll
;         for (int ai = 0; ai < 2; ++ai)
; #pragma unroll
;             for (int m = 0; m < 4; ++m) { bf16* rowp = O + (size_t)(row0 + ai * 128 + m * 16) * FF + col0;
;                 float hv[8];
; #pragma unroll
;                 for (int n = 0; n < 2; ++n)
; #pragma unroll
;                     for (int j = 0; j < 4; ++j) { const float g = acc[ai][0][m][n][j], up = acc[ai][1][m][n][j]; hv[4 * n + j] = g * __builtin_amdgcn_rcpf(1.f + __expf(-g)) * up; }
;                 v4u w; w.x = pg8::cvt_pk_bf16(hv[0], hv[1]); w.y = pg8::cvt_pk_bf16(hv[2], hv[3]); w.z = pg8::cvt_pk_bf16(hv[4], hv[5]); w.w = pg8::cvt_pk_bf16(hv[6], hv[7]);
;                 *(v4u*)rowp = w; }
	v_mul_f32_e32 v90, v168, v90
	v_mul_f32_e32 v91, v169, v91
	v_mul_f32_e32 v93, v171, v81
	v_mul_f32_e32 v86, v172, v82
	v_mul_f32_e32 v83, v173, v83
	v_mul_f32_e32 v72, v76, v72
	v_mul_f32_e32 v73, v175, v73
	v_mul_f32_e32 v74, v176, v74
	v_mul_f32_e32 v75, v177, v75
	v_mul_f32_e32 v77, v179, v65
	v_mul_f32_e32 v70, v180, v66
	v_mul_f32_e32 v67, v181, v67
	v_mul_f32_e32 v150, 0xbfb8aa3b, v60
	v_mul_f32_e32 v154, 0xbfb8aa3b, v52
	v_mul_f32_e32 v158, 0xbfb8aa3b, v44
	v_mul_f32_e32 v162, 0xbfb8aa3b, v36
	v_mul_f32_e32 v166, 0xbfb8aa3b, v28
	v_mul_f32_e32 v170, 0xbfb8aa3b, v20
	v_mul_f32_e32 v174, 0xbfb8aa3b, v12
	v_mul_f32_e32 v178, 0xbfb8aa3b, v4
	v_mul_f32_e32 v124, v156, v114
	v_lshlrev_b64 v[112:113], 1, v[146:147]
	v_cvt_pk_bf16_f32 v115, v122, v123
	v_cvt_pk_bf16_f32 v116, v116, v117
	v_mul_f32_e32 v108, v100, v96
	v_cvt_pk_bf16_f32 v97, v106, v107
	v_cvt_pk_bf16_f32 v99, v102, v99
	v_mul_f32_e32 v92, v84, v80
	v_cvt_pk_bf16_f32 v81, v90, v91
	v_cvt_pk_bf16_f32 v83, v86, v83
	v_mul_f32_e32 v76, v68, v64
	v_cvt_pk_bf16_f32 v65, v74, v75
	v_cvt_pk_bf16_f32 v67, v70, v67
	v_exp_f32_e32 v150, v150
	v_mul_f32_e32 v151, 0xbfb8aa3b, v61
	v_mul_f32_e32 v152, 0xbfb8aa3b, v62
	v_mul_f32_e32 v153, 0xbfb8aa3b, v63
	v_exp_f32_e32 v154, v154
	v_mul_f32_e32 v155, 0xbfb8aa3b, v53
	v_mul_f32_e32 v157, 0xbfb8aa3b, v55
	v_exp_f32_e32 v158, v158
	v_mul_f32_e32 v159, 0xbfb8aa3b, v45
	v_mul_f32_e32 v160, 0xbfb8aa3b, v46
	v_mul_f32_e32 v161, 0xbfb8aa3b, v47
	v_exp_f32_e32 v162, v162
	v_mul_f32_e32 v163, 0xbfb8aa3b, v37
	v_mul_f32_e32 v164, 0xbfb8aa3b, v38
	v_mul_f32_e32 v165, 0xbfb8aa3b, v39
	v_exp_f32_e32 v166, v166
	v_mul_f32_e32 v167, 0xbfb8aa3b, v29
	v_mul_f32_e32 v168, 0xbfb8aa3b, v30
	v_mul_f32_e32 v169, 0xbfb8aa3b, v31
	v_exp_f32_e32 v170, v170
	v_mul_f32_e32 v171, 0xbfb8aa3b, v21
	v_mul_f32_e32 v172, 0xbfb8aa3b, v22
	v_mul_f32_e32 v173, 0xbfb8aa3b, v23
	v_exp_f32_e32 v174, v174
	v_mul_f32_e32 v175, 0xbfb8aa3b, v13
	v_mul_f32_e32 v176, 0xbfb8aa3b, v14
	v_mul_f32_e32 v177, 0xbfb8aa3b, v15
	v_exp_f32_e32 v178, v178
	v_mul_f32_e32 v179, 0xbfb8aa3b, v5
	v_mul_f32_e32 v180, 0xbfb8aa3b, v6
	v_mul_f32_e32 v181, 0xbfb8aa3b, v7
	v_cvt_pk_bf16_f32 v114, v120, v121
	v_lshl_add_u64 v[118:119], v[148:149], 0, v[112:113]
	v_cvt_pk_bf16_f32 v117, v124, v125
	v_cvt_pk_bf16_f32 v96, v104, v105
	v_cvt_pk_bf16_f32 v98, v108, v109
	v_cvt_pk_bf16_f32 v80, v88, v89
	v_cvt_pk_bf16_f32 v82, v92, v93
	v_cvt_pk_bf16_f32 v64, v72, v73
	v_cvt_pk_bf16_f32 v66, v76, v77
	v_add_f32_e32 v150, 1.0, v150
	v_exp_f32_e32 v151, v151
	v_exp_f32_e32 v152, v152
	v_exp_f32_e32 v153, v153
	v_add_f32_e32 v154, 1.0, v154
	v_exp_f32_e32 v155, v155
	v_mul_f32_e32 v156, 0xbfb8aa3b, v54
	v_exp_f32_e32 v157, v157
	v_add_f32_e32 v158, 1.0, v158
	v_exp_f32_e32 v159, v159
	v_exp_f32_e32 v160, v160
	v_exp_f32_e32 v161, v161
	v_add_f32_e32 v162, 1.0, v162
	v_exp_f32_e32 v163, v163
	v_exp_f32_e32 v164, v164
	v_exp_f32_e32 v165, v165
	v_add_f32_e32 v166, 1.0, v166
	v_exp_f32_e32 v167, v167
	v_exp_f32_e32 v168, v168
	v_exp_f32_e32 v169, v169
	v_add_f32_e32 v170, 1.0, v170
	v_exp_f32_e32 v171, v171
	v_exp_f32_e32 v172, v172
	v_exp_f32_e32 v173, v173
	v_add_f32_e32 v174, 1.0, v174
	v_exp_f32_e32 v175, v175
	v_exp_f32_e32 v176, v176
	v_exp_f32_e32 v177, v177
	v_add_f32_e32 v178, 1.0, v178
	v_exp_f32_e32 v179, v179
	v_exp_f32_e32 v180, v180
	v_exp_f32_e32 v181, v181
	global_store_dwordx4 v[118:119], v[114:117], off
	v_rcp_f32_e32 v150, v150
	v_add_f32_e32 v151, 1.0, v151
	v_add_f32_e32 v152, 1.0, v152
	v_add_f32_e32 v153, 1.0, v153
	v_rcp_f32_e32 v154, v154
	v_add_f32_e32 v155, 1.0, v155
	v_exp_f32_e32 v156, v156
	v_add_f32_e32 v157, 1.0, v157
	v_rcp_f32_e32 v158, v158
	v_add_f32_e32 v159, 1.0, v159
	v_add_f32_e32 v160, 1.0, v160
	v_add_f32_e32 v161, 1.0, v161
	v_rcp_f32_e32 v162, v162
	v_add_f32_e32 v163, 1.0, v163
	v_add_f32_e32 v164, 1.0, v164
	v_add_f32_e32 v165, 1.0, v165
	v_rcp_f32_e32 v166, v166
	v_add_f32_e32 v167, 1.0, v167
	v_add_f32_e32 v168, 1.0, v168
	v_add_f32_e32 v169, 1.0, v169
	v_rcp_f32_e32 v170, v170
	v_add_f32_e32 v171, 1.0, v171
	v_add_f32_e32 v172, 1.0, v172
	v_add_f32_e32 v173, 1.0, v173
	v_rcp_f32_e32 v174, v174
	v_add_f32_e32 v175, 1.0, v175
	v_add_f32_e32 v176, 1.0, v176
	v_add_f32_e32 v177, 1.0, v177
	v_rcp_f32_e32 v178, v178
	v_add_f32_e32 v179, 1.0, v179
	v_add_f32_e32 v180, 1.0, v180
	v_add_f32_e32 v181, 1.0, v181
	v_or_b32_e32 v114, 16, v144
	v_mul_f32_e32 v60, v60, v150
	v_rcp_f32_e32 v151, v151
	v_rcp_f32_e32 v152, v152
; __device__ __forceinline__ unsigned cvt_pk_bf16(float lo, float hi) { unsigned r; asm volatile("v_cvt_pk_bf16_f32 %0, %1, %2" : "=v"(r) : "v"(lo), "v"(hi)); return r; }
;     DI void operator()(const pg8::f32x4 (&acc)[2][2][4][2], const pg8::Unit& u, int wr, int wc, int fr, int fq) const {
;         const int row0 = u.pm * 256 + wr * 64 + fr, col0 = u.pn * 128 + wc * 32 + 8 * fq;
; #pragma unroll
;         for (int ai = 0; ai < 2; ++ai)
; #pragma unroll
;             for (int m = 0; m < 4; ++m) { bf16* rowp = O + (size_t)(row0 + ai * 128 + m * 16) * FF + col0;
;                 float hv[8];
; #pragma unroll
;                 for (int n = 0; n < 2; ++n)
; #pragma unroll
;                     for (int j = 0; j < 4; ++j) { const float g = acc[ai][0][m][n][j], up = acc[ai][1][m][n][j]; hv[4 * n + j] = g * __builtin_amdgcn_rcpf(1.f + __expf(-g)) * up; }
;                 v4u w; w.x = pg8::cvt_pk_bf16(hv[0], hv[1]); w.y = pg8::cvt_pk_bf16(hv[2], hv[3]); w.z = pg8::cvt_pk_bf16(hv[4], hv[5]); w.w = pg8::cvt_pk_bf16(hv[6], hv[7]);
;                 *(v4u*)rowp = w; }
	v_rcp_f32_e32 v153, v153
	v_mul_f32_e32 v52, v52, v154
	v_rcp_f32_e32 v155, v155
	v_add_f32_e32 v156, 1.0, v156
	v_rcp_f32_e32 v157, v157
	v_mul_f32_e32 v44, v44, v158
	v_rcp_f32_e32 v159, v159
	v_rcp_f32_e32 v160, v160
	v_rcp_f32_e32 v161, v161
	v_mul_f32_e32 v36, v36, v162
	v_rcp_f32_e32 v163, v163
	v_rcp_f32_e32 v164, v164
	v_rcp_f32_e32 v165, v165
	v_mul_f32_e32 v28, v28, v166
	v_rcp_f32_e32 v167, v167
	v_rcp_f32_e32 v168, v168
	v_rcp_f32_e32 v169, v169
	v_mul_f32_e32 v20, v20, v170
	v_rcp_f32_e32 v171, v171
	v_rcp_f32_e32 v172, v172
	v_rcp_f32_e32 v173, v173
	v_mul_f32_e32 v12, v12, v174
	v_rcp_f32_e32 v175, v175
	v_rcp_f32_e32 v176, v176
	v_rcp_f32_e32 v177, v177
	v_mul_f32_e32 v4, v4, v178
	v_rcp_f32_e32 v179, v179
	v_rcp_f32_e32 v180, v180
	v_rcp_f32_e32 v181, v181
	v_mad_i64_i32 v[114:115], s[14:15], v114, s7, v[138:139]
	v_mul_f32_e32 v56, v60, v56
	v_mul_f32_e32 v151, v61, v151
	v_mul_f32_e32 v152, v62, v152
	v_mul_f32_e32 v153, v63, v153
	v_mul_f32_e32 v155, v53, v155
	v_rcp_f32_e32 v156, v156
	v_mul_f32_e32 v157, v55, v157
	v_mul_f32_e32 v40, v44, v40
	v_mul_f32_e32 v159, v45, v159
	v_mul_f32_e32 v160, v46, v160
	v_mul_f32_e32 v161, v47, v161
	v_mul_f32_e32 v163, v37, v163
	v_mul_f32_e32 v164, v38, v164
	v_mul_f32_e32 v165, v39, v165
	v_mul_f32_e32 v24, v28, v24
	v_mul_f32_e32 v167, v29, v167
	v_mul_f32_e32 v168, v30, v168
	v_mul_f32_e32 v169, v31, v169
	v_mul_f32_e32 v171, v21, v171
	v_mul_f32_e32 v172, v22, v172
	v_mul_f32_e32 v173, v23, v173
	v_mul_f32_e32 v8, v12, v8
	v_mul_f32_e32 v175, v13, v175
	v_mul_f32_e32 v176, v14, v176
	v_mul_f32_e32 v177, v15, v177
	v_mul_f32_e32 v179, v5, v179
	v_mul_f32_e32 v180, v6, v180
	v_mul_f32_e32 v181, v7, v181
	v_lshl_add_u64 v[100:101], v[114:115], 0, v[112:113]
	v_mul_f32_e32 v57, v151, v57
	v_mul_f32_e32 v58, v152, v58
	v_mul_f32_e32 v59, v153, v59
	v_mul_f32_e32 v60, v52, v48
	v_mul_f32_e32 v61, v155, v49
	v_mul_f32_e32 v156, v54, v156
	v_mul_f32_e32 v51, v157, v51
	v_mul_f32_e32 v41, v159, v41
	v_mul_f32_e32 v42, v160, v42
	v_mul_f32_e32 v43, v161, v43
	v_mul_f32_e32 v44, v36, v32
	v_mul_f32_e32 v45, v163, v33
	v_mul_f32_e32 v38, v164, v34
	v_mul_f32_e32 v35, v165, v35
	v_mul_f32_e32 v25, v167, v25
	v_mul_f32_e32 v26, v168, v26
	v_mul_f32_e32 v27, v169, v27
	v_mul_f32_e32 v28, v20, v16
	v_mul_f32_e32 v29, v171, v17
	v_mul_f32_e32 v22, v172, v18
	v_mul_f32_e32 v19, v173, v19
	v_mul_f32_e32 v9, v175, v9
	v_mul_f32_e32 v10, v176, v10
	v_mul_f32_e32 v11, v177, v11
	v_mul_f32_e32 v12, v4, v0
	v_mul_f32_e32 v13, v179, v1
	v_mul_f32_e32 v6, v180, v2
	v_mul_f32_e32 v3, v181, v3
	global_store_dwordx4 v[100:101], v[96:99], off
	v_mul_f32_e32 v54, v156, v50
	v_cvt_pk_bf16_f32 v48, v56, v57
	v_cvt_pk_bf16_f32 v49, v58, v59
	v_cvt_pk_bf16_f32 v32, v40, v41
	v_cvt_pk_bf16_f32 v33, v42, v43
	v_cvt_pk_bf16_f32 v34, v44, v45
	v_cvt_pk_bf16_f32 v35, v38, v35
	v_cvt_pk_bf16_f32 v16, v24, v25
	v_cvt_pk_bf16_f32 v17, v26, v27
	v_cvt_pk_bf16_f32 v18, v28, v29
	v_cvt_pk_bf16_f32 v19, v22, v19
	v_cvt_pk_bf16_f32 v0, v8, v9
	v_cvt_pk_bf16_f32 v1, v10, v11
	v_cvt_pk_bf16_f32 v2, v12, v13
	v_cvt_pk_bf16_f32 v3, v6, v3
	v_or_b32_e32 v96, 32, v144
	v_cvt_pk_bf16_f32 v50, v60, v61
	v_cvt_pk_bf16_f32 v51, v54, v51
	v_mad_i64_i32 v[96:97], s[14:15], v96, s7, v[138:139]
	v_lshl_add_u64 v[84:85], v[96:97], 0, v[112:113]
	global_store_dwordx4 v[84:85], v[80:83], off
	s_nop 0
	s_nop 0
	v_or_b32_e32 v80, 48, v144
	v_mad_i64_i32 v[80:81], s[14:15], v80, s7, v[138:139]
	v_lshl_add_u64 v[68:69], v[80:81], 0, v[112:113]
	global_store_dwordx4 v[68:69], v[64:67], off
	s_nop 0
	s_nop 0
	v_add_u32_e32 v64, 0x80, v144
	v_mad_i64_i32 v[64:65], s[14:15], v64, s7, v[138:139]
	v_lshl_add_u64 v[52:53], v[64:65], 0, v[112:113]
	global_store_dwordx4 v[52:53], v[48:51], off
	s_nop 0
	s_nop 0
	v_add_u32_e32 v48, 0x90, v144
	v_mad_i64_i32 v[48:49], s[14:15], v48, s7, v[138:139]
	v_lshl_add_u64 v[36:37], v[48:49], 0, v[112:113]
	global_store_dwordx4 v[36:37], v[32:35], off
	s_nop 0
	s_nop 0
	v_add_u32_e32 v32, 0xa0, v144
	v_mad_i64_i32 v[32:33], s[14:15], v32, s7, v[138:139]
	v_lshl_add_u64 v[20:21], v[32:33], 0, v[112:113]
	global_store_dwordx4 v[20:21], v[16:19], off
	s_nop 0
	s_nop 0
	v_add_u32_e32 v16, 0xb0, v144
	v_mad_i64_i32 v[16:17], s[14:15], v16, s7, v[138:139]
	s_mov_b64 s[14:15], -1
	v_lshl_add_u64 v[4:5], v[16:17], 0, v[112:113]
	global_store_dwordx4 v[4:5], v[0:3], off
	s_cbranch_vccnz .LBB0_1172
	s_andn2_b64 vcc, exec, s[0:1]
	s_cbranch_vccnz .LBB0_1171
	s_barrier
	s_branch .LBB0_1171
